# helper look-ahead raised from 5 to 8 records with the faster scan step
# baseline (speedup 1.0000x reference)
.Lpf_poll:
	global_load_dword v20, v0, s[98:99] sc1
	s_waitcnt vmcnt(0)
	v_readfirstlane_b32 s17, v20
	s_nop 3
	s_add_i32 s17, s17, 8
	s_min_u32 s17, s17, 63
	s_cmp_gt_u32 s6, s17
	s_cbranch_scc1 .Lpf_wait
